# NSA K-tile LDS swizzle widened to (row&15)<<4 so ds_read_b128 lane groups are bank-conflict-free on CDNA4 (writers+readers, 7 masks)
# speedup vs baseline: 1.0030x; 1.0030x over previous
; DI void nsa_attention(int L2, char* lds, int vcu, int G, int tid, int wave, int lane) {
;     ...
;     const int r32 = lane & 31, hi = lane >> 5, tl = r32 >> 2, r = r32 & 3;
;     float* ws = (float*)(lds + NSL_WS) + wave * 64;
;     bf16_t* stg = (bf16_t*)(lds + NSL_OST) + wave * (32 * 136);
;     float* imp = (float*)(lds + NSL_IMP) + wave * 512;
;     unsigned long long* selm = (unsigned long long*)(lds + NSL_SEL);
;     constexpr float C = 0.088388347648318440f * 1.4426950408889634f;
;     const int nper = (G == 256) ? 4 : (1024 + G - 1) / G;
;     ...
;             int tid2 = tid, lane2 = lane; asm volatile("" : "+v"(tid2), "+v"(lane2));
;             const int r32b = lane2 & 31, hib = lane2 >> 5;
.LBB0_807:
	s_cmp_lt_i32 s68, 1
	s_cbranch_scc1 .LBB0_900
	s_and_b32 s69, s89, 15
	s_xor_b32 s6, s69, 31
	v_readlane_b32 s12, v255, 12
	v_writelane_b32 v255, s6, 29
	s_or_b32 s6, s69, 32
	v_writelane_b32 v255, s6, 30
	s_xor_b32 s6, s69, 63
	v_and_b32_e32 v150, 7, v165
	s_ashr_i32 s3, s2, 6
	v_bfe_u32 v2, v165, 5, 1
	v_writelane_b32 v255, s6, 31
	v_cmp_eq_u32_e64 s[14:15], 0, v150
	s_lshl_b32 s4, s3, 8
	v_lshlrev_b32_e32 v4, 2, v2
	v_writelane_b32 v255, s14, 32
	s_add_i32 s11, s4, 0
	s_mul_i32 s4, s3, 0x2200
	s_lshl_b32 s5, s3, 11
	s_lshl_b32 s71, s3, 3
	v_or_b32_e32 v7, 1, v4
	v_mov_b32_e32 v9, 0x990
	s_movk_i32 s3, 0x110
	v_mov_b32_e32 v10, 0x1320
	v_writelane_b32 v255, s15, 33
	v_mul_u32_u24_e32 v8, 0x110, v7
	v_mad_u32_u24 v9, v7, s3, v9
	v_mad_u32_u24 v7, v7, s3, v10
	s_andn2_b32 s2, s2, 63
	v_readlane_b32 s3, v255, 13
	v_bfe_u32 v3, v165, 2, 3
	v_and_b32_e32 v152, 56, v165
	s_add_i32 s2, s3, s2
	v_add_u32_e32 v240, s2, v152
	v_lshl_add_u32 v241, v3, 3, s2
	v_readlane_b32 s2, v255, 14
	v_writelane_b32 v255, s66, 23
	s_add_i32 s4, s4, 0
	v_and_b32_e32 v0, 31, v165
	v_writelane_b32 v255, s67, 24
	v_writelane_b32 v255, s63, 27
	s_add_i32 s11, s11, 0x25000
	s_add_i32 s4, s4, 0x10000
	v_writelane_b32 v255, s64, 34
	v_lshl_add_u32 v180, v0, 2, s11
	v_lshl_add_u32 v5, v0, 1, s4
	v_lshlrev_b32_e32 v183, 8, v0
	v_lshlrev_b32_e32 v0, 4, v165
	v_writelane_b32 v255, s65, 35
	v_and_b32_e32 v184, 0xf0, v0
	v_lshlrev_b32_e32 v0, 5, v165
	v_writelane_b32 v255, s68, 36
	v_and_b32_e32 v167, 63, v165
	s_add_i32 s10, s12, s5
	s_ashr_i32 s70, s89, 4
	v_and_b32_e32 v11, 0x700, v0
	v_lshlrev_b32_e32 v0, 2, v150
	v_writelane_b32 v255, s69, 37
	v_add3_u32 v185, s10, v11, v0
	v_lshlrev_b32_e32 v0, 3, v167
	v_writelane_b32 v255, s70, 38
	v_cmp_gt_u32_e64 s[76:77], 32, v167
	v_add_u32_e32 v254, s3, v0
	v_bfe_u32 v242, v165, 4, 2
	v_and_b32_e32 v0, 0x78, v0
	v_writelane_b32 v255, s71, 39
	v_and_b32_e32 v178, 3, v165
	v_or_b32_e32 v179, s71, v3
	v_lshlrev_b32_e32 v148, 3, v2
	v_lshlrev_b32_e32 v181, 4, v2
	v_mul_u32_u24_e32 v6, 0x440, v2
	v_lshlrev_b32_e32 v10, 8, v3
	v_lshl_add_u32 v3, v0, 1, s4
	v_mul_u32_u24_e32 v12, 0x110, v242
	v_or_b32_e32 v154, 8, v150
	v_or_b32_e32 v156, 16, v150
	v_or_b32_e32 v158, 24, v150
	v_or_b32_e32 v160, 32, v150
	v_or_b32_e32 v162, 40, v150
	v_or_b32_e32 v164, 48, v150
	v_or_b32_e32 v166, 56, v167
	v_lshl_add_u32 v191, v2, 6, v246
	v_or_b32_e32 v2, s5, v11
	v_writelane_b32 v255, s76, 40
	v_cmp_lt_u32_e64 s[6:7], 31, v167
	v_add_u32_e32 v182, s11, v181
	s_mov_b32 s78, 0
	v_cmp_eq_u32_e64 s[8:9], 0, v178
	v_mov_b32_e32 v149, v150
	v_mov_b32_e32 v151, v154
	v_mov_b32_e32 v153, v156
	v_mov_b32_e32 v155, v158
	v_mov_b32_e32 v157, v160
	v_mov_b32_e32 v159, v162
	v_mov_b32_e32 v161, v164
	v_mov_b32_e32 v163, v166
	v_or3_b32 v190, s5, v10, v4
	v_add_u32_e32 v192, s2, v2
	v_add_u32_e32 v193, s12, v2
	v_add_u32_e32 v198, v3, v12
	v_lshlrev_b32_e32 v168, 1, v0
	v_add_u32_e32 v199, v5, v6
	v_add_u32_e32 v200, v5, v8
	v_add_u32_e32 v201, v5, v9
	v_add_u32_e32 v202, v5, v7
	v_writelane_b32 v255, s77, 41
	s_branch .LBB0_811

; template <int I> DI const float* arg_in() { return (const float*)karg_u64<8 * I>(); }
; DI unsigned char* arg_ws() { return (unsigned char*)karg_u64<200>(); }
; template <int D> DI void qnorm_rope(att::Core<D>& c, const float* gain, const float* tab, int hi) {
;     constexpr int ND = D / 16, HALFR = D / 8;
;     float x[ND][8]; float ss = 0.f;
; #pragma unroll
;     for (int d0 = 0; d0 < ND; ++d0) { const u32x4 w = __builtin_bit_cast(u32x4, c.qr[d0]);
;         x[d0][0] = bflo(w.x); x[d0][1] = bfhi(w.x); x[d0][2] = bflo(w.y); x[d0][3] = bfhi(w.y); x[d0][4] = bflo(w.z); x[d0][5] = bfhi(w.z); x[d0][6] = bflo(w.w); x[d0][7] = bfhi(w.w);
; #pragma unroll
;         for (int e = 0; e < 8; ++e) ss += x[d0][e] * x[d0][e]; }
; DI void nsa_attention(int L2, char* lds, int vcu, int G, int tid, int wave, int lane) {
;     ...
;         const int b = bg >> 2, g = bg & 3, t0 = qt * 64, t = t0 + 8 * wave + tl, h = 4 * g + r;
;         const bf16_t* rowp = NSA_QKV + (size_t)(b * T + t) * NS_N;
;         att::Core<128> c;
;         att::load_q<128>(c, rowp + h * 128, hi);
;         qnorm_rope<128>(c, arg_in<15>() + L2 * 128, (const float*)(arg_ws() + WS_ROPE128) + (size_t)(b * T + t) * 32, hi);
.LBB0_820:
	s_mov_b64 s[12:13], -1
	s_and_b64 vcc, exec, s[2:3]
	s_cbranch_vccz .LBB0_810
	s_ashr_i32 s28, s4, 2
	s_and_b32 s30, s4, 3
	s_lshl_b32 s86, s91, 6
	v_add_u32_e32 v169, s86, v179
	s_lshl_b32 s80, s30, 2
	s_lshl_b32 s79, s28, 12
	v_or_b32_e32 v203, s80, v178
	s_load_dwordx2 s[2:3], s[0:1], 0xc8
	s_waitcnt lgkmcnt(0)
	v_add_u32_e32 v170, s79, v169
	v_mov_b64_e32 v[2:3], s[2:3]
	v_mad_i64_i32 v[2:3], s[2:3], v170, s33, v[2:3]
	v_lshlrev_b32_e32 v0, 8, v203
	v_lshl_add_u64 v[2:3], v[2:3], 0, v[0:1]
	v_lshlrev_b32_e32 v0, 1, v148
	v_lshl_add_u64 v[2:3], v[2:3], 0, v[0:1]
	v_add_co_u32_e32 v4, vcc, s73, v2
	s_mov_b64 s[2:3], 0x2fb00000
	s_nop 0
	v_addc_co_u32_e32 v5, vcc, 0, v3, vcc
	global_load_dwordx4 v[42:45], v[4:5], off
	v_lshl_add_u64 v[2:3], v[2:3], 0, s[2:3]
	global_load_dwordx4 v[46:49], v[2:3], off offset:32
	global_load_dwordx4 v[38:41], v[2:3], off offset:64
	global_load_dwordx4 v[34:37], v[2:3], off offset:96
	global_load_dwordx4 v[30:33], v[2:3], off offset:128
	global_load_dwordx4 v[18:21], v[2:3], off offset:160
	global_load_dwordx4 v[14:17], v[2:3], off offset:192
	global_load_dwordx4 v[10:13], v[2:3], off offset:224
	v_ashrrev_i32_e32 v171, 31, v170
	s_lshl_b64 s[2:3], s[66:67], 2
	v_lshlrev_b64 v[4:5], 7, v[170:171]
	v_lshlrev_b32_e32 v0, 2, v148
	s_load_dwordx2 s[4:5], s[0:1], 0x78
	s_waitcnt lgkmcnt(0)
	s_load_dwordx2 s[12:13], s[0:1], 0xc8
	s_waitcnt lgkmcnt(0)
	s_add_u32 s2, s4, s2
	v_lshl_add_u64 v[2:3], s[12:13], 0, v[4:5]
	s_addc_u32 s3, s5, s3
	v_lshl_add_u64 v[22:23], v[2:3], 0, v[0:1]
	s_mov_b64 s[4:5], 0x27700000
	v_lshl_add_u64 v[50:51], v[22:23], 0, s[4:5]
	s_mov_b32 s4, 0x27700000
	v_add_co_u32_e32 v22, vcc, s4, v22
	global_load_dwordx4 v[2:5], v0, s[2:3] offset:16
	global_load_dwordx4 v[6:9], v0, s[2:3] offset:80
	v_addc_co_u32_e32 v23, vcc, 0, v23, vcc
	global_load_dwordx4 v[26:29], v[22:23], off
	s_nop 0
	global_load_dwordx4 v[22:25], v[50:51], off offset:80
	s_movk_i32 s10, 0xf0
	s_ashr_i32 s29, s28, 31
	s_lshl_b64 s[12:13], s[28:29], 18
	s_waitcnt vmcnt(0)
	v_lshlrev_b32_e32 v90, 16, v46
	v_and_b32_e32 v83, 0xffff0000, v42
	v_lshlrev_b32_e32 v82, 16, v42
	v_mul_f32_e32 v42, v83, v83
	v_lshlrev_b32_e32 v84, 16, v43
	v_fmac_f32_e32 v42, v82, v82
	v_and_b32_e32 v85, 0xffff0000, v43
	v_fmac_f32_e32 v42, v84, v84
	v_lshlrev_b32_e32 v86, 16, v44
	v_fmac_f32_e32 v42, v85, v85
	v_and_b32_e32 v87, 0xffff0000, v44
	v_fmac_f32_e32 v42, v86, v86
	v_lshlrev_b32_e32 v88, 16, v45
	v_fmac_f32_e32 v42, v87, v87
	v_and_b32_e32 v89, 0xffff0000, v45
	v_fmac_f32_e32 v42, v88, v88
	v_fmac_f32_e32 v42, v89, v89
	v_and_b32_e32 v91, 0xffff0000, v46
	v_fmac_f32_e32 v42, v90, v90
	v_lshlrev_b32_e32 v92, 16, v47
	v_fmac_f32_e32 v42, v91, v91
	v_and_b32_e32 v93, 0xffff0000, v47
	v_fmac_f32_e32 v42, v92, v92
	v_lshlrev_b32_e32 v94, 16, v48
	v_fmac_f32_e32 v42, v93, v93
	v_and_b32_e32 v95, 0xffff0000, v48
	v_fmac_f32_e32 v42, v94, v94
	v_lshlrev_b32_e32 v96, 16, v49
	v_fmac_f32_e32 v42, v95, v95
	v_and_b32_e32 v97, 0xffff0000, v49
	v_fmac_f32_e32 v42, v96, v96
	v_lshlrev_b32_e32 v98, 16, v38
	v_fmac_f32_e32 v42, v97, v97
	v_and_b32_e32 v99, 0xffff0000, v38
	v_fmac_f32_e32 v42, v98, v98
	v_lshlrev_b32_e32 v100, 16, v39
	v_fmac_f32_e32 v42, v99, v99
	v_and_b32_e32 v101, 0xffff0000, v39
	v_fmac_f32_e32 v42, v100, v100
	v_lshlrev_b32_e32 v102, 16, v40
	v_fmac_f32_e32 v42, v101, v101
	v_and_b32_e32 v103, 0xffff0000, v40
	v_fmac_f32_e32 v42, v102, v102
	v_lshlrev_b32_e32 v104, 16, v41
	v_fmac_f32_e32 v42, v103, v103
	v_and_b32_e32 v105, 0xffff0000, v41
	v_fmac_f32_e32 v42, v104, v104
	v_lshlrev_b32_e32 v106, 16, v34
	v_fmac_f32_e32 v42, v105, v105
	v_and_b32_e32 v107, 0xffff0000, v34
	v_fmac_f32_e32 v42, v106, v106
	v_lshlrev_b32_e32 v108, 16, v35
	v_fmac_f32_e32 v42, v107, v107
	v_and_b32_e32 v109, 0xffff0000, v35
	v_fmac_f32_e32 v42, v108, v108
	v_lshlrev_b32_e32 v110, 16, v36
	v_fmac_f32_e32 v42, v109, v109
	v_and_b32_e32 v111, 0xffff0000, v36
	v_fmac_f32_e32 v42, v110, v110
	v_lshlrev_b32_e32 v112, 16, v37
	v_fmac_f32_e32 v42, v111, v111
	v_and_b32_e32 v113, 0xffff0000, v37
	v_lshlrev_b32_e32 v114, 16, v30
	v_and_b32_e32 v115, 0xffff0000, v30
	v_lshlrev_b32_e32 v116, 16, v31
	v_and_b32_e32 v117, 0xffff0000, v31
	v_lshlrev_b32_e32 v118, 16, v32
	v_and_b32_e32 v119, 0xffff0000, v32
	v_lshlrev_b32_e32 v120, 16, v33
	v_and_b32_e32 v121, 0xffff0000, v33
	v_fmac_f32_e32 v42, v112, v112
	global_load_dwordx4 v[30:33], v[50:51], off offset:16
	v_fmac_f32_e32 v42, v113, v113
	v_fmac_f32_e32 v42, v114, v114
	v_fmac_f32_e32 v42, v115, v115
	v_fmac_f32_e32 v42, v116, v116
	v_fmac_f32_e32 v42, v117, v117
	v_fmac_f32_e32 v42, v118, v118
	v_fmac_f32_e32 v42, v119, v119
	v_fmac_f32_e32 v42, v120, v120
	v_fmac_f32_e32 v42, v121, v121
	v_lshlrev_b32_e32 v122, 16, v18
	v_and_b32_e32 v123, 0xffff0000, v18
	v_fmac_f32_e32 v42, v122, v122
	v_lshlrev_b32_e32 v124, 16, v19
	v_and_b32_e32 v125, 0xffff0000, v19
	v_lshlrev_b32_e32 v126, 16, v20
	v_and_b32_e32 v127, 0xffff0000, v20
	v_lshlrev_b32_e32 v128, 16, v21
	v_and_b32_e32 v129, 0xffff0000, v21
	v_fmac_f32_e32 v42, v123, v123
	global_load_dwordx4 v[18:21], v0, s[2:3]
	global_load_dwordx4 v[34:37], v[50:51], off offset:64
	global_load_dwordx4 v[38:41], v0, s[2:3] offset:64
	v_fmac_f32_e32 v42, v124, v124
	v_fmac_f32_e32 v42, v125, v125
	v_fmac_f32_e32 v42, v126, v126
	v_fmac_f32_e32 v42, v127, v127
	v_fmac_f32_e32 v42, v128, v128
	v_fmac_f32_e32 v42, v129, v129
	v_lshlrev_b32_e32 v130, 16, v14
	v_and_b32_e32 v131, 0xffff0000, v14
	v_fmac_f32_e32 v42, v130, v130
	v_lshlrev_b32_e32 v132, 16, v15
	v_fmac_f32_e32 v42, v131, v131
	v_and_b32_e32 v133, 0xffff0000, v15
	v_fmac_f32_e32 v42, v132, v132
; #define GAS __attribute__((address_space(1)))
; DI unsigned cvtpk(float lo, float hi) { unsigned r; asm volatile("v_cvt_pk_bf16_f32 %0, %1, %2" : "=v"(r) : "v"(lo), "v"(hi)); return r; }
; DI float sum_xor32(float s) { auto r = __builtin_amdgcn_permlane32_swap(__float_as_uint(s), __float_as_uint(s), false, false); return __uint_as_float(r[0]) + __uint_as_float(r[1]); }
; template <int D> DI void qnorm_rope(att::Core<D>& c, const float* gain, const float* tab, int hi) {
;     ...
;     ss = sum_xor32(ss);
;     const float rs = __builtin_amdgcn_rsqf(ss * (1.0f / D) + EPS);
; #pragma unroll
;     for (int d0 = 0; d0 < ND; ++d0) { const f32x4 ga = *(const GAS f32x4*)(gain + d0 * 16 + hi * 8), gb = *(const GAS f32x4*)(gain + d0 * 16 + hi * 8 + 4);
; #pragma unroll
;         for (int e = 0; e < 8; ++e) x[d0][e] = x[d0][e] * rs * (e < 4 ? ga[e] : gb[e - 4]); }
;     if constexpr (D == 64) {
;         const f32x4 ca = *(const GAS f32x4*)(tab), cb = *(const GAS f32x4*)(tab + 4), sa = *(const GAS f32x4*)(tab + HALFR), sb = *(const GAS f32x4*)(tab + HALFR + 4);
; #pragma unroll
;         for (int e = 0; e < 8; ++e) { const float cs = e < 4 ? ca[e] : cb[e - 4], sn = e < 4 ? sa[e] : sb[e - 4];
;             auto rr = __builtin_amdgcn_permlane32_swap(__float_as_uint(x[0][e]), __float_as_uint(x[0][e]), false, false);
;             const float y = __uint_as_float(hi ? rr[0] : rr[1]);
;             x[0][e] = hi ? (x[0][e] * cs + y * sn) : (x[0][e] * cs - y * sn); }
;     } else {
;         const f32x4 ca = *(const GAS f32x4*)(tab + hi * 8), cb = *(const GAS f32x4*)(tab + hi * 8 + 4), sa = *(const GAS f32x4*)(tab + HALFR + hi * 8), sb = *(const GAS f32x4*)(tab + HALFR + hi * 8 + 4);
; #pragma unroll
;         for (int e = 0; e < 8; ++e) { const float cs = e < 4 ? ca[e] : cb[e - 4], sn = e < 4 ? sa[e] : sb[e - 4];
;             const float x1 = x[0][e], x2 = x[1][e]; x[0][e] = x1 * cs - x2 * sn; x[1][e] = x2 * cs + x1 * sn; }
;     }
; #pragma unroll
;     for (int d0 = 0; d0 < ND; ++d0) { u32x4 w; w.x = cvtpk(x[d0][0], x[d0][1]); w.y = cvtpk(x[d0][2], x[d0][3]); w.z = cvtpk(x[d0][4], x[d0][5]); w.w = cvtpk(x[d0][6], x[d0][7]); c.qr[d0] = __builtin_bit_cast(bf16x8, w); }
	v_lshlrev_b32_e32 v134, 16, v16
	v_fmac_f32_e32 v42, v133, v133
	v_and_b32_e32 v135, 0xffff0000, v16
	v_fmac_f32_e32 v42, v134, v134
	v_lshlrev_b32_e32 v136, 16, v17
	v_fmac_f32_e32 v42, v135, v135
	v_and_b32_e32 v137, 0xffff0000, v17
	v_fmac_f32_e32 v42, v136, v136
	v_fmac_f32_e32 v42, v137, v137
	v_lshlrev_b32_e32 v138, 16, v10
	v_and_b32_e32 v139, 0xffff0000, v10
	v_lshlrev_b32_e32 v140, 16, v11
	v_and_b32_e32 v141, 0xffff0000, v11
	v_lshlrev_b32_e32 v142, 16, v12
	v_and_b32_e32 v143, 0xffff0000, v12
	v_lshlrev_b32_e32 v144, 16, v13
	v_and_b32_e32 v145, 0xffff0000, v13
	v_fmac_f32_e32 v42, v138, v138
	global_load_dwordx4 v[10:13], v0, s[2:3] offset:448
	global_load_dwordx4 v[14:17], v0, s[2:3] offset:464
	v_fmac_f32_e32 v42, v139, v139
	v_fmac_f32_e32 v42, v140, v140
	v_fmac_f32_e32 v42, v141, v141
	v_fmac_f32_e32 v42, v142, v142
	v_fmac_f32_e32 v42, v143, v143
	v_fmac_f32_e32 v42, v144, v144
	v_fmac_f32_e32 v42, v145, v145
	v_mov_b32_e32 v43, v42
	s_nop 1
	v_permlane32_swap_b32_e32 v42, v43
	v_add_f32_e32 v42, v42, v43
	v_fmamk_f32 v42, v42, 0x3c000000, v243
	v_rsq_f32_e32 v146, v42
	global_load_dwordx4 v[42:45], v0, s[2:3] offset:128
	global_load_dwordx4 v[46:49], v0, s[2:3] offset:144
	global_load_dwordx4 v[50:53], v0, s[2:3] offset:384
	global_load_dwordx4 v[54:57], v0, s[2:3] offset:400
	global_load_dwordx4 v[58:61], v0, s[2:3] offset:192
	global_load_dwordx4 v[62:65], v0, s[2:3] offset:208
	global_load_dwordx4 v[66:69], v0, s[2:3] offset:256
	global_load_dwordx4 v[70:73], v0, s[2:3] offset:272
	global_load_dwordx4 v[74:77], v0, s[2:3] offset:320
	global_load_dwordx4 v[78:81], v0, s[2:3] offset:336
	s_lshl_b32 s2, s91, 2
	s_addk_i32 s2, 0x42
	v_mul_f32_e32 v0, v146, v88
	v_mul_f32_e32 v0, v4, v0
	v_mul_f32_e32 v88, v146, v96
	v_mul_f32_e32 v4, v0, v24
	v_mul_f32_e32 v8, v8, v88
	s_lshr_b32 s14, s2, 6
	s_waitcnt vmcnt(15)
	v_fmac_f32_e32 v4, v8, v32
	v_mul_f32_e32 v8, v8, v24
	v_fma_f32 v0, v0, v32, -v8
	v_mul_f32_e32 v8, v146, v87
	v_mul_f32_e32 v3, v3, v8
	v_mul_f32_e32 v24, v146, v95
	v_mul_f32_e32 v8, v3, v23
	v_mul_f32_e32 v7, v7, v24
	v_fmac_f32_e32 v8, v7, v31
	v_mul_f32_e32 v7, v7, v23
	v_fma_f32 v3, v3, v31, -v7
	v_mul_f32_e32 v7, v146, v86
	v_mul_f32_e32 v2, v2, v7
	v_mul_f32_e32 v23, v146, v94
	v_mul_f32_e32 v7, v2, v22
	v_mul_f32_e32 v6, v6, v23
	v_fmac_f32_e32 v7, v6, v30
	v_mul_f32_e32 v6, v6, v22
	v_fma_f32 v2, v2, v30, -v6
	v_mul_f32_e32 v6, v146, v85
	s_waitcnt vmcnt(14)
	v_mul_f32_e32 v6, v21, v6
	v_mul_f32_e32 v22, v146, v93
	s_waitcnt vmcnt(13)
	v_mul_f32_e32 v21, v6, v37
	s_waitcnt vmcnt(12)
	v_mul_f32_e32 v22, v41, v22
	v_fmac_f32_e32 v21, v22, v29
	v_mul_f32_e32 v22, v22, v37
	v_fma_f32 v6, v6, v29, -v22
	v_mul_f32_e32 v22, v146, v84
	v_mul_f32_e32 v20, v20, v22
	v_mul_f32_e32 v23, v146, v92
	v_mul_f32_e32 v22, v20, v36
	v_mul_f32_e32 v23, v40, v23
	v_fmac_f32_e32 v22, v23, v28
	v_mul_f32_e32 v23, v23, v36
	v_fma_f32 v20, v20, v28, -v23
	v_mul_f32_e32 v23, v146, v83
	v_mul_f32_e32 v19, v19, v23
	v_mul_f32_e32 v24, v146, v91
	v_mul_f32_e32 v23, v19, v35
	v_mul_f32_e32 v24, v39, v24
	v_fmac_f32_e32 v23, v24, v27
	v_mul_f32_e32 v24, v24, v35
	v_fma_f32 v19, v19, v27, -v24
	v_mul_f32_e32 v24, v146, v82
	v_mul_f32_e32 v18, v18, v24
	v_mul_f32_e32 v27, v146, v90
	v_mul_f32_e32 v24, v18, v34
	v_mul_f32_e32 v27, v38, v27
	v_fmac_f32_e32 v24, v27, v26
	v_mul_f32_e32 v27, v27, v34
	v_fma_f32 v18, v18, v26, -v27
	v_mul_f32_e32 v26, v146, v145
	v_mul_f32_e32 v27, v146, v136
	s_waitcnt vmcnt(10)
	v_mul_f32_e32 v17, v26, v17
	v_mul_f32_e32 v26, v146, v144
	v_mul_f32_e32 v16, v26, v16
	v_mul_f32_e32 v26, v146, v143
	v_mul_f32_e32 v15, v26, v15
	v_mul_f32_e32 v26, v146, v142
	v_mul_f32_e32 v14, v26, v14
	v_mul_f32_e32 v26, v146, v141
	v_mul_f32_e32 v13, v26, v13
	v_mul_f32_e32 v26, v146, v140
	v_mul_f32_e32 v12, v26, v12
	v_mul_f32_e32 v26, v146, v139
	v_mul_f32_e32 v11, v26, v11
	v_mul_f32_e32 v26, v146, v138
	v_mul_f32_e32 v10, v26, v10
	v_mul_f32_e32 v26, v146, v137
	s_waitcnt vmcnt(6)
	v_mul_f32_e32 v26, v26, v57
	v_mul_f32_e32 v57, v146, v115
	s_waitcnt vmcnt(3)
	v_mul_f32_e32 v57, v57, v67
	v_mul_f32_e32 v67, v146, v114
	v_mul_f32_e32 v66, v67, v66
	v_mul_f32_e32 v67, v146, v113
	v_mul_f32_e32 v65, v67, v65
	v_mul_f32_e32 v67, v146, v112
	v_mul_f32_e32 v64, v67, v64
	v_mul_f32_e32 v67, v146, v111
	v_mul_f32_e32 v63, v67, v63
	v_mul_f32_e32 v67, v146, v110
	v_mul_f32_e32 v62, v67, v62
	v_mul_f32_e32 v67, v146, v109
	v_mul_f32_e32 v61, v67, v61
	v_mul_f32_e32 v67, v146, v108
	v_mul_f32_e32 v60, v67, v60
	v_mul_f32_e32 v67, v146, v107
	v_mul_f32_e32 v59, v67, v59
	v_mul_f32_e32 v67, v146, v106
	v_mul_f32_e32 v58, v67, v58
	v_mul_f32_e32 v67, v146, v105
	v_mul_f32_e32 v49, v67, v49
	v_mul_f32_e32 v67, v146, v104
	v_mul_f32_e32 v48, v67, v48
	v_mul_f32_e32 v67, v146, v103
	v_mul_f32_e32 v47, v67, v47
	v_mul_f32_e32 v67, v146, v102
	v_mul_f32_e32 v46, v67, v46
	v_mul_f32_e32 v67, v146, v101
	v_mul_f32_e32 v45, v45, v67
	v_mul_f32_e32 v67, v146, v100
	v_mul_f32_e32 v44, v44, v67
	v_mul_f32_e32 v67, v146, v99
	v_mul_f32_e32 v43, v43, v67
	v_mul_f32_e32 v67, v146, v98
	v_mul_f32_e32 v42, v42, v67
	v_mul_f32_e32 v67, v146, v97
	v_mul_f32_e32 v9, v9, v67
	v_mul_f32_e32 v67, v146, v89
	v_mul_f32_e32 v5, v5, v67
	v_mul_f32_e32 v67, v9, v25
	v_mul_f32_e32 v28, v146, v135
	v_mul_f32_e32 v29, v146, v134
	v_mul_f32_e32 v30, v146, v133
	v_mul_f32_e32 v31, v146, v132
	v_mul_f32_e32 v32, v146, v131
	v_mul_f32_e32 v34, v146, v130
	v_fma_f32 v67, v5, v33, -v67
	v_mul_f32_e32 v5, v5, v25
	v_mul_f32_e32 v27, v27, v56
	v_mul_f32_e32 v28, v28, v55
	v_mul_f32_e32 v29, v29, v54
	v_mul_f32_e32 v30, v30, v53
	v_mul_f32_e32 v31, v31, v52
	v_mul_f32_e32 v32, v32, v51
	v_mul_f32_e32 v34, v34, v50
	v_mul_f32_e32 v35, v146, v129
	v_mul_f32_e32 v36, v146, v128
	v_mul_f32_e32 v37, v146, v127
	v_mul_f32_e32 v38, v146, v126
	v_mul_f32_e32 v39, v146, v125
	v_mul_f32_e32 v40, v146, v124
	v_mul_f32_e32 v41, v146, v123
	v_mul_f32_e32 v50, v146, v122
	v_mul_f32_e32 v51, v146, v121
	v_mul_f32_e32 v52, v146, v120
	v_mul_f32_e32 v53, v146, v119
	v_mul_f32_e32 v54, v146, v118
	v_mul_f32_e32 v55, v146, v117
	v_mul_f32_e32 v56, v146, v116
	v_fmac_f32_e32 v5, v9, v33
	v_cvt_pk_bf16_f32 v112, v18, v19
	v_cvt_pk_bf16_f32 v113, v20, v6
	v_cvt_pk_bf16_f32 v114, v2, v3
	v_cvt_pk_bf16_f32 v115, v0, v67
	v_mov_b32_e32 v0, v165
	v_mov_b32_e32 v6, v167
	s_waitcnt vmcnt(0)
; DI unsigned cvtpk(float lo, float hi) { unsigned r; asm volatile("v_cvt_pk_bf16_f32 %0, %1, %2" : "=v"(r) : "v"(lo), "v"(hi)); return r; }
; DI int v_rd_base(int lane) { return ((lane & 3) << 3) | (((lane >> 2) & 3) << 6) | (((lane >> 4) & 1) << 5) | (((lane >> 5) & 1) << 8); }
; template <int D> DI void qnorm_rope(att::Core<D>& c, const float* gain, const float* tab, int hi) {
;     ...
;     for (int d0 = 0; d0 < ND; ++d0) { u32x4 w; w.x = cvtpk(x[d0][0], x[d0][1]); w.y = cvtpk(x[d0][2], x[d0][3]); w.z = cvtpk(x[d0][4], x[d0][5]); w.w = cvtpk(x[d0][6], x[d0][7]); c.qr[d0] = __builtin_bit_cast(bf16x8, w); }
; DI void nsa_attention(int L2, char* lds, int vcu, int G, int tid, int wave, int lane) {
;     ...
;             int tid2 = tid, lane2 = lane; asm volatile("" : "+v"(tid2), "+v"(lane2));
;             const int r32b = lane2 & 31, hib = lane2 >> 5;
;             {
;                 const bf16_t* Kc = NSA_KC + (size_t)b * 256 * 512 + g * 128; const bf16_t* Vc = NSA_VC + (size_t)b * 256 * 512 + g * 128;
; #pragma unroll 1
;                 for (int j0 = 0; j0 < ncmp_tiles; ++j0) {
;                     att::StgH<128> k0, v0;
;                     att::stg_ld<128>(k0, Kc + (size_t)64 * j0 * 512, 512, tid2); att::stg_ld<128>(v0, Vc + (size_t)64 * j0 * 512, 512, tid2);
;                     att::stg_wrK<128>(k0, lds + NSL_KV + j0 * 16384, tid2); att::stg_wrV<128>(v0, lds + NSL_OST + j0 * 16384, tid2);
;                 }
;             }
;             __syncthreads();
;             att::core_reset<128>(c, att::M_INIT, 0.f);
;             MaskCmp mk; mk.t = t;
;             const int vbc = (int)(uintptr_t)(lds + NSL_OST) + att::v_rd_base(lane2);
	v_mul_f32_e32 v35, v35, v81
	v_mul_f32_e32 v36, v36, v80
	v_mul_f32_e32 v37, v37, v79
	v_mul_f32_e32 v38, v38, v78
	v_mul_f32_e32 v39, v39, v77
	v_mul_f32_e32 v40, v40, v76
	v_mul_f32_e32 v41, v41, v75
	v_mul_f32_e32 v50, v50, v74
	v_mul_f32_e32 v51, v51, v73
	v_mul_f32_e32 v52, v52, v72
	v_mul_f32_e32 v53, v53, v71
	v_mul_f32_e32 v54, v54, v70
	v_mul_f32_e32 v55, v55, v69
	v_mul_f32_e32 v56, v56, v68
	v_cvt_pk_bf16_f32 v116, v24, v23
	v_cvt_pk_bf16_f32 v117, v22, v21
	v_cvt_pk_bf16_f32 v118, v7, v8
	v_cvt_pk_bf16_f32 v119, v4, v5
	v_cvt_pk_bf16_f32 v120, v42, v43
	v_cvt_pk_bf16_f32 v121, v44, v45
	v_cvt_pk_bf16_f32 v122, v46, v47
	v_cvt_pk_bf16_f32 v123, v48, v49
	v_cvt_pk_bf16_f32 v124, v58, v59
	v_cvt_pk_bf16_f32 v125, v60, v61
	v_cvt_pk_bf16_f32 v126, v62, v63
	v_cvt_pk_bf16_f32 v127, v64, v65
	v_cvt_pk_bf16_f32 v128, v66, v57
	v_cvt_pk_bf16_f32 v129, v56, v55
	v_cvt_pk_bf16_f32 v130, v54, v53
	v_cvt_pk_bf16_f32 v131, v52, v51
	v_cvt_pk_bf16_f32 v132, v50, v41
	v_cvt_pk_bf16_f32 v133, v40, v39
	v_cvt_pk_bf16_f32 v134, v38, v37
	v_cvt_pk_bf16_f32 v135, v36, v35
	v_cvt_pk_bf16_f32 v136, v34, v32
	v_cvt_pk_bf16_f32 v137, v31, v30
	v_cvt_pk_bf16_f32 v138, v29, v28
	v_cvt_pk_bf16_f32 v139, v27, v26
	v_cvt_pk_bf16_f32 v140, v10, v11
	v_cvt_pk_bf16_f32 v141, v12, v13
	v_cvt_pk_bf16_f32 v142, v14, v15
	v_cvt_pk_bf16_f32 v143, v16, v17
	s_load_dwordx2 s[2:3], s[0:1], 0xc8
	s_waitcnt lgkmcnt(0)
	s_load_dwordx2 s[4:5], s[0:1], 0xc8
	s_waitcnt lgkmcnt(0)
	s_nop 0
	v_ashrrev_i32_e32 v2, 4, v0
	v_lshlrev_b32_e32 v5, 4, v0
	v_and_b32_e32 v7, 0xf0, v0
	v_bitop3_b32 v9, v5, v7, s10 bitop3:0x6c
	v_and_b32_e32 v7, 0xfffff0, v2
	v_lshlrev_b32_e32 v8, 1, v2
	v_add_u32_e32 v4, 32, v2
	v_and_or_b32 v7, v8, 8, v7
	v_lshrrev_b32_e32 v8, 1, v7
	v_and_b32_e32 v7, 0xfffff0, v4
	v_lshlrev_b32_e32 v4, 1, v4
	v_and_or_b32 v4, v4, 8, v7
	v_bfe_u32 v10, v0, 2, 2
	v_lshrrev_b32_e32 v4, 1, v4
	v_lshlrev_b32_e32 v7, 5, v2
	v_or_b32_e32 v4, v4, v10
	v_and_b32_e32 v12, 0x100, v7
	v_lshlrev_b32_e32 v7, 6, v2
	v_and_b32_e32 v11, 48, v5
	v_lshl_or_b32 v4, v4, 9, v12
	v_and_b32_e32 v13, 0xc0, v7
	v_or3_b32 v4, v4, v13, v11
	v_add_u32_e32 v7, 0x10000, v4
	v_or_b32_e32 v4, v8, v10
	v_ashrrev_i32_e32 v3, 31, v2
	v_lshl_or_b32 v4, v4, 9, v12
	v_or3_b32 v4, v4, v13, v11
	s_movk_i32 s10, 0xff00
	v_lshlrev_b64 v[2:3], 10, v[2:3]
	v_add_u32_e32 v8, 0x10000, v4
	v_and_or_b32 v9, v5, s10, v9
	v_lshl_add_u64 v[4:5], s[12:13], 0, v[2:3]
	v_and_b32_e32 v0, 15, v0
	v_lshl_or_b32 v4, s30, 8, v4
	v_lshlrev_b32_e32 v0, 4, v0
	v_lshl_add_u64 v[2:3], s[4:5], 0, v[4:5]
	v_lshl_add_u64 v[4:5], s[2:3], 0, v[4:5]
	s_mov_b32 s2, s14
	s_mov_b64 s[4:5], 0x10000
.LBB0_822:
	v_lshl_add_u64 v[14:15], v[4:5], 0, v[0:1]
	v_add_co_u32_e32 v10, vcc, 0x3eb00000, v14
	v_lshl_add_u64 v[22:23], v[2:3], 0, v[0:1]
	s_nop 0
	v_addc_co_u32_e32 v11, vcc, 0, v15, vcc
	v_add_co_u32_e32 v14, vcc, 0x3eb08000, v14
	global_load_dwordx4 v[10:13], v[10:11], off
	s_nop 0
	v_addc_co_u32_e32 v15, vcc, 0, v15, vcc
	v_add_co_u32_e32 v18, vcc, 0x3ec00000, v22
	global_load_dwordx4 v[14:17], v[14:15], off
	s_nop 0
	v_addc_co_u32_e32 v19, vcc, 0, v23, vcc
	v_add_co_u32_e32 v22, vcc, 0x3ec08000, v22
	global_load_dwordx4 v[18:21], v[18:19], off
	s_nop 0
	v_addc_co_u32_e32 v23, vcc, 0, v23, vcc
	global_load_dwordx4 v[22:25], v[22:23], off
	v_add_u32_e32 v26, 0, v9
	s_add_i32 s2, s2, -1
	v_add_u32_e32 v9, 0x4000, v9
	v_lshl_add_u64 v[2:3], v[2:3], 0, s[4:5]
	v_lshl_add_u64 v[4:5], v[4:5], 0, s[4:5]
	s_cmp_eq_u32 s2, 0
	s_waitcnt vmcnt(3)
	ds_write_b128 v26, v[10:13]
	s_waitcnt vmcnt(2)
	ds_write_b128 v26, v[14:17] offset:8192
	v_add_u32_e32 v10, 0, v8
	v_add_u32_e32 v8, 0x4000, v8
	s_waitcnt vmcnt(1)
	ds_write_b128 v10, v[18:21]
	v_add_u32_e32 v10, 0, v7
	v_add_u32_e32 v7, 0x4000, v7
	s_waitcnt vmcnt(0)
	ds_write_b128 v10, v[22:25]
	s_cbranch_scc0 .LBB0_822
	s_add_i32 s2, 0, 0x10000
	v_lshlrev_b32_e32 v3, 3, v6
	s_cmp_lg_u32 s2, -1
	v_and_b32_e32 v0, 31, v6
	v_lshlrev_b32_e32 v4, 1, v6
	v_and_b32_e32 v3, 0x118, v3
	v_lshlrev_b32_e32 v5, 4, v6
	s_cselect_b32 s2, s2, 0
	v_ashrrev_i32_e32 v2, 5, v6
	v_and_b32_e32 v4, 32, v4
	v_and_b32_e32 v7, 0xc0, v5
	v_lshlrev_b32_e32 v144, 8, v0
	v_lshl_add_u32 v177, v0, 2, s11
	v_add_u32_e32 v0, s2, v3
	v_mov_b32_e32 v14, v1
	v_mov_b32_e32 v15, v1
	v_and_b32_e32 v145, 0xf0, v5
	v_lshlrev_b32_e32 v146, 4, v2
	v_cmp_gt_u32_e64 s[12:13], 32, v6
	v_lshl_add_u32 v204, v2, 6, v246
	v_add3_u32 v205, v0, v7, v4
	v_mov_b32_e32 v0, v1
	v_mov_b32_e32 v2, v1
	v_mov_b32_e32 v3, v1
	v_mov_b32_e32 v4, v1
	v_mov_b32_e32 v5, v1
	v_mov_b32_e32 v6, v1
	v_mov_b32_e32 v7, v1
	v_mov_b32_e32 v8, v1
	v_mov_b32_e32 v9, v1
	v_mov_b32_e32 v10, v1
	v_mov_b32_e32 v11, v1
	v_mov_b32_e32 v12, v1
	v_mov_b32_e32 v13, v1
	v_mov_b64_e32 v[30:31], v[14:15]
	v_mov_b64_e32 v[46:47], v[14:15]
	v_mov_b64_e32 v[62:63], v[14:15]
	v_mov_b64_e32 v[78:79], v[14:15]
	v_add_u32_e32 v147, 32, v146
	v_add_u32_e32 v171, 64, v146
	v_add_u32_e32 v172, 0x60, v146
	v_add_u32_e32 v173, 0x80, v146
	v_add_u32_e32 v174, 0xa0, v146
	v_add_u32_e32 v175, 0xc0, v146
	v_add_u32_e32 v176, 0xe0, v146
	s_mov_b32 s4, 0
	v_mov_b32_e32 v206, 0xc6ea6000
	v_mov_b32_e32 v207, 0
	s_mov_b32 s5, s14
	v_mov_b64_e32 v[28:29], v[12:13]
	v_mov_b64_e32 v[26:27], v[10:11]
	v_mov_b64_e32 v[24:25], v[8:9]
	v_mov_b64_e32 v[22:23], v[6:7]
	v_mov_b64_e32 v[20:21], v[4:5]
	v_mov_b64_e32 v[18:19], v[2:3]
	v_mov_b64_e32 v[16:17], v[0:1]
	v_mov_b64_e32 v[44:45], v[12:13]
	v_mov_b64_e32 v[42:43], v[10:11]
	v_mov_b64_e32 v[40:41], v[8:9]
	v_mov_b64_e32 v[38:39], v[6:7]
	v_mov_b64_e32 v[36:37], v[4:5]
	v_mov_b64_e32 v[34:35], v[2:3]
	v_mov_b64_e32 v[32:33], v[0:1]
	v_mov_b64_e32 v[60:61], v[12:13]
	v_mov_b64_e32 v[58:59], v[10:11]
	v_mov_b64_e32 v[56:57], v[8:9]
	v_mov_b64_e32 v[54:55], v[6:7]
	v_mov_b64_e32 v[52:53], v[4:5]
	v_mov_b64_e32 v[50:51], v[2:3]
	v_mov_b64_e32 v[48:49], v[0:1]
	v_mov_b64_e32 v[76:77], v[12:13]
	v_mov_b64_e32 v[74:75], v[10:11]
	v_mov_b64_e32 v[72:73], v[8:9]
	v_mov_b64_e32 v[70:71], v[6:7]
	v_mov_b64_e32 v[68:69], v[4:5]
	v_mov_b64_e32 v[66:67], v[2:3]
	v_mov_b64_e32 v[64:65], v[0:1]
	s_waitcnt lgkmcnt(0)
	s_barrier

; DI int v_rd_base(int lane) { return ((lane & 3) << 3) | (((lane >> 2) & 3) << 6) | (((lane >> 4) & 1) << 5) | (((lane >> 5) & 1) << 8); }
; #define LBAR() asm volatile("s_waitcnt lgkmcnt(0)\n\ts_barrier" ::: "memory")
; template <int D, bool PIPE, class Seq, class MaskF, class KX>
; DI void run_tiles(Core<D>& c, char* kv, float* ws, const bf16_t* Kg0, const bf16_t* Vg0, int pitch, const Seq& seq, const MaskF& mk, const KX& kx, int tid_, int lane_) {
;     ...
;     int t0; if (!seq.first(t0)) return;
;     const int vb0 = (int)(uintptr_t)(kv + 2 * KB) + v_rd_base(lane);
;     StgH<D> sk, sv;
;     if constexpr (!PIPE) {
;         stg_ld<D>(sk, Kg0 + (size_t)64 * t0 * pitch, pitch, tid); stg_ld<D>(sv, Vg0 + (size_t)64 * t0 * pitch, pitch, tid);
;         LBAR();
;         kx.apply(sk, t0, tid); stg_wrK<D>(sk, kv, tid); stg_wrV<D>(sv, kv + 2 * KB, tid);
;         LBAR();
; DI void nsa_attention(int L2, char* lds, int vcu, int G, int tid, int wave, int lane) {
;     ...
;             att::core_reset<128>(c, att::M_INIT, 0.f);
;             SeqBits seq; seq.bits = usel;
;             MaskSel mk; mk.t = t; mk.qt = qt; mk.sel = mysel;
;             att::run_tiles<128, false>(c, lds + NSL_KV, ws, NSA_QKV + (size_t)b * T * NS_N + NS_KS + g * 128, NSA_QKV + (size_t)b * T * NS_N + NS_VS + g * 128, NS_N, seq, mk, KxNone(), tid, lane);
.LBB0_858:
	s_lshl_b32 s56, s30, 7
	s_mul_hi_i32 s49, s28, 0x1400000
	s_mul_i32 s48, s28, 0x1400000
	v_mov_b32_e32 v3, v165
	v_mov_b32_e32 v2, v167
	s_cmp_eq_u64 s[50:51], 0
	s_load_dwordx2 s[12:13], s[0:1], 0xc8
	s_waitcnt lgkmcnt(0)
	s_load_dwordx2 s[2:3], s[0:1], 0xc8
	s_waitcnt lgkmcnt(0)
	s_cbranch_scc1 .LBB0_876
	s_lshl_b64 s[14:15], s[48:49], 1
	s_add_u32 s4, s12, s14
	s_addc_u32 s5, s13, s15
	s_lshl_b32 s10, s56, 1
	s_add_u32 s4, s4, s10
	s_addc_u32 s5, s5, 0
	s_add_u32 s4, s4, 0x2fb01800
	s_addc_u32 s5, s5, 0
	s_add_u32 s2, s2, s14
	s_addc_u32 s3, s3, s15
	s_add_u32 s2, s2, s10
	s_addc_u32 s3, s3, 0
	s_add_u32 s57, s2, 0x2fb01c00
	s_ff1_i32_b64 s59, s[50:51]
	v_ashrrev_i32_e32 v8, 4, v3
	s_addc_u32 s58, s3, 0
	s_mul_i32 s10, s59, 0xa0000
	s_movk_i32 s14, 0x1400
	v_add_u32_e32 v10, 32, v8
	s_add_u32 s2, s4, s10
	v_lshlrev_b32_e32 v9, 3, v3
	v_mad_i64_i32 v[4:5], s[12:13], v8, s14, 0
	v_mad_i64_i32 v[6:7], s[12:13], v10, s14, 0
	s_addc_u32 s3, s5, 0
	v_and_b32_e32 v16, 0x78, v9
	v_lshlrev_b64 v[172:173], 1, v[4:5]
	v_lshlrev_b64 v[174:175], 1, v[6:7]
	v_lshl_add_u64 v[4:5], s[2:3], 0, v[172:173]
	v_lshlrev_b32_e32 v0, 1, v16
	v_lshl_add_u64 v[6:7], s[2:3], 0, v[174:175]
	s_add_u32 s2, s57, s10
	v_lshl_add_u64 v[4:5], v[4:5], 0, v[0:1]
	s_addc_u32 s3, s58, 0
	v_lshl_add_u64 v[6:7], v[6:7], 0, v[0:1]
	global_load_dwordx4 v[98:101], v[4:5], off
	global_load_dwordx4 v[102:105], v[6:7], off
	v_lshl_add_u64 v[4:5], s[2:3], 0, v[172:173]
	v_lshl_add_u64 v[4:5], v[4:5], 0, v[0:1]
	v_lshl_add_u64 v[6:7], s[2:3], 0, v[174:175]
	v_lshl_add_u64 v[6:7], v[6:7], 0, v[0:1]
	global_load_dwordx4 v[106:109], v[4:5], off
	global_load_dwordx4 v[144:147], v[6:7], off
	v_ashrrev_i32_e32 v0, 5, v2
	v_and_b32_e32 v4, 31, v2
	v_lshlrev_b32_e32 v6, 4, v2
	v_and_b32_e32 v12, 0xfffff0, v8
	v_lshlrev_b32_e32 v13, 1, v8
	v_lshlrev_b32_e32 v5, 3, v2
	v_lshlrev_b32_e32 v7, 1, v2
	v_lshlrev_b32_e32 v11, 4, v3
	v_and_b32_e32 v3, 0xf0, v3
	v_cmp_gt_u32_e64 s[12:13], 32, v2
	v_and_b32_e32 v2, 0xc0, v6
	s_movk_i32 s2, 0xf0
	v_lshlrev_b32_e32 v171, 8, v4
	v_and_b32_e32 v204, 0xf0, v6
	v_lshlrev_b32_e32 v205, 4, v0
	v_lshlrev_b32_e32 v206, 2, v0
	v_lshl_add_u32 v207, v4, 2, s11
	v_and_or_b32 v0, v13, 8, v12
	v_and_b32_e32 v4, 0xfffff0, v10
	v_lshlrev_b32_e32 v6, 1, v10
	v_bitop3_b32 v3, v11, v3, s2 bitop3:0x6c
	v_lshrrev_b32_e32 v14, 1, v8
	v_bfe_u32 v9, v9, 5, 2
	v_and_b32_e32 v8, 3, v8
	s_movk_i32 s2, 0xff00
	v_lshrrev_b32_e32 v0, 1, v0
	v_and_or_b32 v4, v6, 8, v4
	v_and_or_b32 v208, v11, s2, v3
	v_and_or_b32 v3, v14, 4, v8
	v_or_b32_e32 v0, v0, v9
	v_lshrrev_b32_e32 v4, 1, v4
	v_and_b32_e32 v7, 32, v7
	v_and_b32_e32 v15, 48, v11
	s_movk_i32 s2, 0x118
	v_lshlrev_b32_e32 v3, 6, v3
	v_lshlrev_b32_e32 v0, 9, v0
	v_or_b32_e32 v4, v4, v9
	v_and_or_b32 v5, v5, s2, v7
	v_or3_b32 v214, v0, v3, v15
	v_lshlrev_b32_e32 v0, 9, v4
	s_add_i32 s2, 0, 0x8000
	v_add_u32_e32 v7, 0, v208
	v_or3_b32 v215, v0, v3, v15
	s_cmp_lg_u32 s2, -1
	v_add_u32_e32 v4, 0, v214
	v_add_u32_e32 v0, 0, v215
	s_waitcnt lgkmcnt(0)
	s_barrier
	s_cselect_b32 s2, s2, 0
	v_mov_b32_e32 v14, v1
	v_mov_b32_e32 v15, v1
	v_add3_u32 v216, v2, s2, v5
	v_mov_b32_e32 v2, v1
	v_mov_b32_e32 v3, v1
	v_mov_b32_e32 v5, v1
	v_mov_b32_e32 v6, v1
	v_mov_b32_e32 v8, v1
	v_mov_b32_e32 v9, v1
	s_waitcnt vmcnt(3)
	ds_write_b128 v7, v[98:101]
	s_waitcnt vmcnt(2)
	ds_write_b128 v7, v[102:105] offset:8192
	s_waitcnt vmcnt(1)
	ds_write_b128 v4, v[106:109] offset:32768
	s_waitcnt vmcnt(0)
	ds_write_b128 v0, v[144:147] offset:32768
	s_waitcnt lgkmcnt(0)
	s_barrier
	v_mov_b32_e32 v0, v1
	v_mov_b32_e32 v4, v1
	v_mov_b32_e32 v7, v1
	v_mov_b32_e32 v10, v1
	v_mov_b32_e32 v11, v1
	v_mov_b32_e32 v12, v1
	v_mov_b32_e32 v13, v1
	v_mov_b64_e32 v[64:65], v[14:15]
	v_mov_b64_e32 v[48:49], v[14:15]
	v_mov_b64_e32 v[32:33], v[14:15]
	v_lshlrev_b32_e32 v176, 1, v16
	v_mov_b64_e32 v[62:63], v[12:13]
	v_mov_b64_e32 v[60:61], v[10:11]
	v_mov_b64_e32 v[58:59], v[8:9]
	v_mov_b64_e32 v[56:57], v[6:7]
	v_mov_b64_e32 v[54:55], v[4:5]
	v_mov_b64_e32 v[52:53], v[2:3]
	v_mov_b64_e32 v[50:51], v[0:1]
	v_mov_b64_e32 v[46:47], v[12:13]
	v_mov_b64_e32 v[44:45], v[10:11]
	v_mov_b64_e32 v[42:43], v[8:9]
	v_mov_b64_e32 v[40:41], v[6:7]
	v_mov_b64_e32 v[38:39], v[4:5]
	v_mov_b64_e32 v[36:37], v[2:3]
	v_mov_b64_e32 v[34:35], v[0:1]
	v_mov_b64_e32 v[30:31], v[12:13]
	v_mov_b64_e32 v[28:29], v[10:11]
	v_mov_b64_e32 v[26:27], v[8:9]
	v_mov_b64_e32 v[24:25], v[6:7]
	v_mov_b64_e32 v[22:23], v[4:5]
	v_mov_b64_e32 v[20:21], v[2:3]
	v_mov_b64_e32 v[18:19], v[0:1]
	v_mov_b64_e32 v[16:17], v[14:15]
	s_mov_b32 s10, 0
	v_add_u32_e32 v209, 0x80, v205
	v_add_u32_e32 v210, 0xa0, v205
	v_add_u32_e32 v211, 0xc0, v205
	v_add_u32_e32 v212, 0xe0, v205
	v_add_u32_e32 v213, s11, v205
	v_mov_b32_e32 v218, 0
	v_mov_b32_e32 v217, 0xc6ea6000
	v_mov_b64_e32 v[14:15], v[12:13]
	v_mov_b64_e32 v[12:13], v[10:11]
	v_mov_b64_e32 v[10:11], v[8:9]
	v_mov_b64_e32 v[8:9], v[6:7]
	v_mov_b64_e32 v[6:7], v[4:5]
	v_mov_b64_e32 v[4:5], v[2:3]
	v_mov_b64_e32 v[2:3], v[0:1]

; DI unsigned short f2bf1(float f) { return (unsigned short)(cvtpk(f, 0.f) & 0xffffu); }
; #define LDS_WAIT() asm volatile("s_waitcnt lgkmcnt(0)" ::: "memory")
; DI int crow(int r, int hi) { return (r & 3) + 8 * (r >> 2) + 4 * hi; }
; DI void nsa_stage_out(att::Core<128>& c, bf16_t* stg, float* ws, float fac, bool first, int r32, int hi) {
;     if (hi == 0) ws[r32] = fac;
;     LDS_WAIT();
; #pragma unroll
;     for (int r = 0; r < 16; ++r) { const int orow = att::crow(r, hi); const float f = ws[orow];
; #pragma unroll
;         for (int d0 = 0; d0 < 4; ++d0) { bf16_t* p = stg + orow * 136 + d0 * 32 + r32; float v = c.o[d0][r] * f; if (!first) v += bf2f(*p); *p = f2bf1(v); } }
;     LDS_WAIT();
; }
.LBB0_879:
	s_or_b64 exec, exec, s[2:3]
	s_waitcnt lgkmcnt(0)
	ds_read_b32 v0, v182
	ds_read_u16 v66, v199
	s_max_i32 s2, s91, 8
	s_add_i32 s92, s2, -8
	v_mov_b32_e32 v67, v165
	s_cmp_gt_i32 s92, s91
	s_waitcnt lgkmcnt(0)
	v_lshlrev_b32_e32 v66, 16, v66
	v_fmac_f32_e32 v66, v50, v0
	v_cvt_pk_bf16_f32 v50, v66, v1
	ds_write_b16 v199, v50
	ds_read_u16 v50, v199 offset:64
	v_mov_b32_e32 v66, v167
	v_mov_b32_e32 v68, 0
	s_waitcnt lgkmcnt(0)
	v_lshlrev_b32_e32 v50, 16, v50
	v_fmac_f32_e32 v50, v34, v0
	v_cvt_pk_bf16_f32 v34, v50, v1
	ds_write_b16 v199, v34 offset:64
	ds_read_u16 v34, v199 offset:128
	v_mov_b32_e32 v50, 0
	s_waitcnt lgkmcnt(0)
	v_lshlrev_b32_e32 v34, 16, v34
	v_fmac_f32_e32 v34, v18, v0
	v_cvt_pk_bf16_f32 v18, v34, v1
	ds_write_b16 v199, v18 offset:128
	ds_read_u16 v18, v199 offset:192
	v_mov_b32_e32 v34, 0
	s_waitcnt lgkmcnt(0)
	v_lshlrev_b32_e32 v18, 16, v18
	v_fmac_f32_e32 v18, v2, v0
	v_cvt_pk_bf16_f32 v0, v18, v1
	ds_write_b16 v199, v0 offset:192
	ds_read_b32 v0, v182 offset:4
	ds_read_u16 v2, v200
	v_mov_b32_e32 v18, 0
	s_waitcnt lgkmcnt(0)
	v_lshlrev_b32_e32 v2, 16, v2
	v_fmac_f32_e32 v2, v51, v0
	v_cvt_pk_bf16_f32 v2, v2, v1
	ds_write_b16 v200, v2
	ds_read_u16 v2, v200 offset:64
	v_mov_b32_e32 v51, 0
	s_waitcnt lgkmcnt(0)
	v_lshlrev_b32_e32 v2, 16, v2
	v_fmac_f32_e32 v2, v35, v0
	v_cvt_pk_bf16_f32 v2, v2, v1
	ds_write_b16 v200, v2 offset:64
	ds_read_u16 v2, v200 offset:128
	v_mov_b32_e32 v35, 0
	s_waitcnt lgkmcnt(0)
	v_lshlrev_b32_e32 v2, 16, v2
	v_fmac_f32_e32 v2, v19, v0
	v_cvt_pk_bf16_f32 v2, v2, v1
	ds_write_b16 v200, v2 offset:128
	ds_read_u16 v2, v200 offset:192
	v_mov_b32_e32 v19, 0
	s_waitcnt lgkmcnt(0)
	v_lshlrev_b32_e32 v2, 16, v2
	v_fmac_f32_e32 v2, v3, v0
	v_cvt_pk_bf16_f32 v0, v2, v1
	ds_write_b16 v200, v0 offset:192
	ds_read_b32 v0, v182 offset:8
	ds_read_u16 v2, v200 offset:272
	v_mov_b32_e32 v3, 0
	s_waitcnt lgkmcnt(0)
	v_lshlrev_b32_e32 v2, 16, v2
	v_fmac_f32_e32 v2, v52, v0
	v_cvt_pk_bf16_f32 v2, v2, v1
	ds_write_b16 v200, v2 offset:272
	ds_read_u16 v2, v200 offset:336
	v_mov_b32_e32 v52, 0
	s_waitcnt lgkmcnt(0)
	v_lshlrev_b32_e32 v2, 16, v2
	v_fmac_f32_e32 v2, v36, v0
	v_cvt_pk_bf16_f32 v2, v2, v1
	ds_write_b16 v200, v2 offset:336
	ds_read_u16 v2, v200 offset:400
	v_mov_b32_e32 v36, 0
	s_waitcnt lgkmcnt(0)
	v_lshlrev_b32_e32 v2, 16, v2
	v_fmac_f32_e32 v2, v20, v0
	v_cvt_pk_bf16_f32 v2, v2, v1
	ds_write_b16 v200, v2 offset:400
	ds_read_u16 v2, v200 offset:464
	v_mov_b32_e32 v20, 0
	s_waitcnt lgkmcnt(0)
	v_lshlrev_b32_e32 v2, 16, v2
	v_fmac_f32_e32 v2, v4, v0
	v_cvt_pk_bf16_f32 v0, v2, v1
	ds_write_b16 v200, v0 offset:464
	ds_read_b32 v0, v182 offset:12
	ds_read_u16 v2, v200 offset:544
	v_mov_b32_e32 v4, 0
	s_waitcnt lgkmcnt(0)
	v_lshlrev_b32_e32 v2, 16, v2
	v_fmac_f32_e32 v2, v53, v0
	v_cvt_pk_bf16_f32 v2, v2, v1
	ds_write_b16 v200, v2 offset:544
	ds_read_u16 v2, v200 offset:608
	v_mov_b32_e32 v53, 0
	s_waitcnt lgkmcnt(0)
	v_lshlrev_b32_e32 v2, 16, v2
	v_fmac_f32_e32 v2, v37, v0
	v_cvt_pk_bf16_f32 v2, v2, v1
	ds_write_b16 v200, v2 offset:608
	ds_read_u16 v2, v200 offset:672
	v_mov_b32_e32 v37, 0
	s_waitcnt lgkmcnt(0)
	v_lshlrev_b32_e32 v2, 16, v2
	v_fmac_f32_e32 v2, v21, v0
	v_cvt_pk_bf16_f32 v2, v2, v1
	ds_write_b16 v200, v2 offset:672
	ds_read_u16 v2, v200 offset:736
	v_mov_b32_e32 v21, 0
	s_waitcnt lgkmcnt(0)
	v_lshlrev_b32_e32 v2, 16, v2
	v_fmac_f32_e32 v2, v5, v0
	v_cvt_pk_bf16_f32 v0, v2, v1
	ds_write_b16 v200, v0 offset:736
	ds_read_b32 v0, v182 offset:32
	ds_read_u16 v2, v200 offset:1904
	v_mov_b32_e32 v5, 0
	s_waitcnt lgkmcnt(0)
	v_lshlrev_b32_e32 v2, 16, v2
	v_fmac_f32_e32 v2, v54, v0
	v_cvt_pk_bf16_f32 v2, v2, v1
	ds_write_b16 v200, v2 offset:1904
	ds_read_u16 v2, v200 offset:1968
	v_mov_b32_e32 v54, 0
	s_waitcnt lgkmcnt(0)
	v_lshlrev_b32_e32 v2, 16, v2
	v_fmac_f32_e32 v2, v38, v0
	v_cvt_pk_bf16_f32 v2, v2, v1
	ds_write_b16 v200, v2 offset:1968
	ds_read_u16 v2, v200 offset:2032
	v_mov_b32_e32 v38, 0
	s_waitcnt lgkmcnt(0)
	v_lshlrev_b32_e32 v2, 16, v2
	v_fmac_f32_e32 v2, v22, v0
	v_cvt_pk_bf16_f32 v2, v2, v1
	ds_write_b16 v200, v2 offset:2032
	ds_read_u16 v2, v200 offset:2096
	v_mov_b32_e32 v22, 0
	s_waitcnt lgkmcnt(0)
	v_lshlrev_b32_e32 v2, 16, v2
	v_fmac_f32_e32 v2, v6, v0
	v_cvt_pk_bf16_f32 v0, v2, v1
	ds_write_b16 v200, v0 offset:2096
	ds_read_b32 v0, v182 offset:36
	ds_read_u16 v2, v200 offset:2176
	v_mov_b32_e32 v6, 0
	s_waitcnt lgkmcnt(0)
	v_lshlrev_b32_e32 v2, 16, v2
	v_fmac_f32_e32 v2, v55, v0
	v_cvt_pk_bf16_f32 v2, v2, v1
	ds_write_b16 v200, v2 offset:2176
	ds_read_u16 v2, v200 offset:2240
	v_mov_b32_e32 v55, 0
	s_waitcnt lgkmcnt(0)
	v_lshlrev_b32_e32 v2, 16, v2
	v_fmac_f32_e32 v2, v39, v0
	v_cvt_pk_bf16_f32 v2, v2, v1
	ds_write_b16 v200, v2 offset:2240
	ds_read_u16 v2, v200 offset:2304
	v_mov_b32_e32 v39, 0
	s_waitcnt lgkmcnt(0)
	v_lshlrev_b32_e32 v2, 16, v2
	v_fmac_f32_e32 v2, v23, v0
	v_cvt_pk_bf16_f32 v2, v2, v1
	ds_write_b16 v200, v2 offset:2304
	ds_read_u16 v2, v200 offset:2368
	v_mov_b32_e32 v23, 0
	s_waitcnt lgkmcnt(0)
	v_lshlrev_b32_e32 v2, 16, v2
	v_fmac_f32_e32 v2, v7, v0
	v_cvt_pk_bf16_f32 v0, v2, v1
	ds_write_b16 v200, v0 offset:2368
	ds_read_b32 v0, v182 offset:40
	ds_read_u16 v2, v200 offset:2448
	v_mov_b32_e32 v7, 0
	s_waitcnt lgkmcnt(0)
	v_lshlrev_b32_e32 v2, 16, v2
	v_fmac_f32_e32 v2, v56, v0
	v_cvt_pk_bf16_f32 v2, v2, v1
	ds_write_b16 v200, v2 offset:2448
	ds_read_u16 v2, v201 offset:64
	v_mov_b32_e32 v56, 0
	s_waitcnt lgkmcnt(0)
	v_lshlrev_b32_e32 v2, 16, v2
	v_fmac_f32_e32 v2, v40, v0
	v_cvt_pk_bf16_f32 v2, v2, v1
	ds_write_b16 v201, v2 offset:64
	ds_read_u16 v2, v201 offset:128
	v_mov_b32_e32 v40, 0
	s_waitcnt lgkmcnt(0)
; DI unsigned short f2bf1(float f) { return (unsigned short)(cvtpk(f, 0.f) & 0xffffu); }
; #define LDS_WAIT() asm volatile("s_waitcnt lgkmcnt(0)" ::: "memory")
; DI int crow(int r, int hi) { return (r & 3) + 8 * (r >> 2) + 4 * hi; }
; DI void nsa_stage_out(att::Core<128>& c, bf16_t* stg, float* ws, float fac, bool first, int r32, int hi) {
;     if (hi == 0) ws[r32] = fac;
;     LDS_WAIT();
; #pragma unroll
;     for (int r = 0; r < 16; ++r) { const int orow = att::crow(r, hi); const float f = ws[orow];
; #pragma unroll
;         for (int d0 = 0; d0 < 4; ++d0) { bf16_t* p = stg + orow * 136 + d0 * 32 + r32; float v = c.o[d0][r] * f; if (!first) v += bf2f(*p); *p = f2bf1(v); } }
;     LDS_WAIT();
; }
	v_lshlrev_b32_e32 v2, 16, v2
	v_fmac_f32_e32 v2, v24, v0
	v_cvt_pk_bf16_f32 v2, v2, v1
	ds_write_b16 v201, v2 offset:128
	ds_read_u16 v2, v201 offset:192
	v_mov_b32_e32 v24, 0
	s_waitcnt lgkmcnt(0)
	v_lshlrev_b32_e32 v2, 16, v2
	v_fmac_f32_e32 v2, v8, v0
	v_cvt_pk_bf16_f32 v0, v2, v1
	ds_write_b16 v201, v0 offset:192
	ds_read_b32 v0, v182 offset:44
	ds_read_u16 v2, v201 offset:272
	v_mov_b32_e32 v8, 0
	s_waitcnt lgkmcnt(0)
	v_lshlrev_b32_e32 v2, 16, v2
	v_fmac_f32_e32 v2, v57, v0
	v_cvt_pk_bf16_f32 v2, v2, v1
	ds_write_b16 v201, v2 offset:272
	ds_read_u16 v2, v201 offset:336
	v_mov_b32_e32 v57, 0
	s_waitcnt lgkmcnt(0)
	v_lshlrev_b32_e32 v2, 16, v2
	v_fmac_f32_e32 v2, v41, v0
	v_cvt_pk_bf16_f32 v2, v2, v1
	ds_write_b16 v201, v2 offset:336
	ds_read_u16 v2, v201 offset:400
	v_mov_b32_e32 v41, 0
	s_waitcnt lgkmcnt(0)
	v_lshlrev_b32_e32 v2, 16, v2
	v_fmac_f32_e32 v2, v25, v0
	v_cvt_pk_bf16_f32 v2, v2, v1
	ds_write_b16 v201, v2 offset:400
	ds_read_u16 v2, v201 offset:464
	v_mov_b32_e32 v25, 0
	s_waitcnt lgkmcnt(0)
	v_lshlrev_b32_e32 v2, 16, v2
	v_fmac_f32_e32 v2, v9, v0
	v_cvt_pk_bf16_f32 v0, v2, v1
	ds_write_b16 v201, v0 offset:464
	ds_read_b32 v0, v182 offset:64
	ds_read_u16 v2, v201 offset:1632
	v_mov_b32_e32 v9, 0
	s_waitcnt lgkmcnt(0)
	v_lshlrev_b32_e32 v2, 16, v2
	v_fmac_f32_e32 v2, v58, v0
	v_cvt_pk_bf16_f32 v2, v2, v1
	ds_write_b16 v201, v2 offset:1632
	ds_read_u16 v2, v201 offset:1696
	v_mov_b32_e32 v58, 0
	s_waitcnt lgkmcnt(0)
	v_lshlrev_b32_e32 v2, 16, v2
	v_fmac_f32_e32 v2, v42, v0
	v_cvt_pk_bf16_f32 v2, v2, v1
	ds_write_b16 v201, v2 offset:1696
	ds_read_u16 v2, v201 offset:1760
	v_mov_b32_e32 v42, 0
	s_waitcnt lgkmcnt(0)
	v_lshlrev_b32_e32 v2, 16, v2
	v_fmac_f32_e32 v2, v26, v0
	v_cvt_pk_bf16_f32 v2, v2, v1
	ds_write_b16 v201, v2 offset:1760
	ds_read_u16 v2, v201 offset:1824
	v_mov_b32_e32 v26, 0
	s_waitcnt lgkmcnt(0)
	v_lshlrev_b32_e32 v2, 16, v2
	v_fmac_f32_e32 v2, v10, v0
	v_cvt_pk_bf16_f32 v0, v2, v1
	ds_write_b16 v201, v0 offset:1824
	ds_read_b32 v0, v182 offset:68
	ds_read_u16 v2, v201 offset:1904
	v_mov_b32_e32 v10, 0
	s_waitcnt lgkmcnt(0)
	v_lshlrev_b32_e32 v2, 16, v2
	v_fmac_f32_e32 v2, v59, v0
	v_cvt_pk_bf16_f32 v2, v2, v1
	ds_write_b16 v201, v2 offset:1904
	ds_read_u16 v2, v201 offset:1968
	v_mov_b32_e32 v59, 0
	s_waitcnt lgkmcnt(0)
	v_lshlrev_b32_e32 v2, 16, v2
	v_fmac_f32_e32 v2, v43, v0
	v_cvt_pk_bf16_f32 v2, v2, v1
	ds_write_b16 v201, v2 offset:1968
	ds_read_u16 v2, v201 offset:2032
	v_mov_b32_e32 v43, 0
	s_waitcnt lgkmcnt(0)
	v_lshlrev_b32_e32 v2, 16, v2
	v_fmac_f32_e32 v2, v27, v0
	v_cvt_pk_bf16_f32 v2, v2, v1
	ds_write_b16 v201, v2 offset:2032
	ds_read_u16 v2, v201 offset:2096
	v_mov_b32_e32 v27, 0
	s_waitcnt lgkmcnt(0)
	v_lshlrev_b32_e32 v2, 16, v2
	v_fmac_f32_e32 v2, v11, v0
	v_cvt_pk_bf16_f32 v0, v2, v1
	ds_write_b16 v201, v0 offset:2096
	ds_read_b32 v0, v182 offset:72
	ds_read_u16 v2, v201 offset:2176
	v_mov_b32_e32 v11, 0
	s_waitcnt lgkmcnt(0)
	v_lshlrev_b32_e32 v2, 16, v2
	v_fmac_f32_e32 v2, v60, v0
	v_cvt_pk_bf16_f32 v2, v2, v1
	ds_write_b16 v201, v2 offset:2176
	ds_read_u16 v2, v201 offset:2240
	v_mov_b32_e32 v60, 0
	s_waitcnt lgkmcnt(0)
	v_lshlrev_b32_e32 v2, 16, v2
	v_fmac_f32_e32 v2, v44, v0
	v_cvt_pk_bf16_f32 v2, v2, v1
	ds_write_b16 v201, v2 offset:2240
	ds_read_u16 v2, v201 offset:2304
	v_mov_b32_e32 v44, 0
	s_waitcnt lgkmcnt(0)
	v_lshlrev_b32_e32 v2, 16, v2
	v_fmac_f32_e32 v2, v28, v0
	v_cvt_pk_bf16_f32 v2, v2, v1
	ds_write_b16 v201, v2 offset:2304
	ds_read_u16 v2, v201 offset:2368
	v_mov_b32_e32 v28, 0
	s_waitcnt lgkmcnt(0)
	v_lshlrev_b32_e32 v2, 16, v2
	v_fmac_f32_e32 v2, v12, v0
	v_cvt_pk_bf16_f32 v0, v2, v1
	ds_write_b16 v201, v0 offset:2368
	ds_read_b32 v0, v182 offset:76
	ds_read_u16 v2, v201 offset:2448
	v_mov_b32_e32 v12, 0
	s_waitcnt lgkmcnt(0)
	v_lshlrev_b32_e32 v2, 16, v2
	v_fmac_f32_e32 v2, v61, v0
	v_cvt_pk_bf16_f32 v2, v2, v1
	ds_write_b16 v201, v2 offset:2448
	ds_read_u16 v2, v202 offset:64
	v_mov_b32_e32 v61, 0
	s_waitcnt lgkmcnt(0)
	v_lshlrev_b32_e32 v2, 16, v2
	v_fmac_f32_e32 v2, v45, v0
	v_cvt_pk_bf16_f32 v2, v2, v1
	ds_write_b16 v202, v2 offset:64
	ds_read_u16 v2, v202 offset:128
	v_mov_b32_e32 v45, 0
	s_waitcnt lgkmcnt(0)
	v_lshlrev_b32_e32 v2, 16, v2
	v_fmac_f32_e32 v2, v29, v0
	v_cvt_pk_bf16_f32 v2, v2, v1
	ds_write_b16 v202, v2 offset:128
	ds_read_u16 v2, v202 offset:192
	v_mov_b32_e32 v29, 0
	s_waitcnt lgkmcnt(0)
	v_lshlrev_b32_e32 v2, 16, v2
	v_fmac_f32_e32 v2, v13, v0
	v_cvt_pk_bf16_f32 v0, v2, v1
	ds_write_b16 v202, v0 offset:192
	ds_read_b32 v0, v182 offset:96
	ds_read_u16 v2, v202 offset:1360
	v_mov_b32_e32 v13, 0
	s_waitcnt lgkmcnt(0)
	v_lshlrev_b32_e32 v2, 16, v2
	v_fmac_f32_e32 v2, v62, v0
	v_cvt_pk_bf16_f32 v2, v2, v1
	ds_write_b16 v202, v2 offset:1360
	ds_read_u16 v2, v202 offset:1424
	v_mov_b32_e32 v62, 0
	s_waitcnt lgkmcnt(0)
	v_lshlrev_b32_e32 v2, 16, v2
	v_fmac_f32_e32 v2, v46, v0
	v_cvt_pk_bf16_f32 v2, v2, v1
	ds_write_b16 v202, v2 offset:1424
	ds_read_u16 v2, v202 offset:1488
	v_mov_b32_e32 v46, 0
	s_waitcnt lgkmcnt(0)
	v_lshlrev_b32_e32 v2, 16, v2
	v_fmac_f32_e32 v2, v30, v0
	v_cvt_pk_bf16_f32 v2, v2, v1
	ds_write_b16 v202, v2 offset:1488
	ds_read_u16 v2, v202 offset:1552
	v_mov_b32_e32 v30, 0
	s_waitcnt lgkmcnt(0)
	v_lshlrev_b32_e32 v2, 16, v2
	v_fmac_f32_e32 v2, v14, v0
	v_cvt_pk_bf16_f32 v0, v2, v1
	ds_write_b16 v202, v0 offset:1552
	ds_read_b32 v0, v182 offset:100
	ds_read_u16 v2, v202 offset:1632
	v_mov_b32_e32 v14, 0
	s_waitcnt lgkmcnt(0)
	v_lshlrev_b32_e32 v2, 16, v2
	v_fmac_f32_e32 v2, v63, v0
	v_cvt_pk_bf16_f32 v2, v2, v1
	ds_write_b16 v202, v2 offset:1632
	ds_read_u16 v2, v202 offset:1696
	v_mov_b32_e32 v63, 0
	s_waitcnt lgkmcnt(0)
; DI unsigned short f2bf1(float f) { return (unsigned short)(cvtpk(f, 0.f) & 0xffffu); }
; #define LDS_WAIT() asm volatile("s_waitcnt lgkmcnt(0)" ::: "memory")
; DI int crow(int r, int hi) { return (r & 3) + 8 * (r >> 2) + 4 * hi; }
; DI void nsa_stage_out(att::Core<128>& c, bf16_t* stg, float* ws, float fac, bool first, int r32, int hi) {
;     if (hi == 0) ws[r32] = fac;
;     LDS_WAIT();
; #pragma unroll
;     for (int r = 0; r < 16; ++r) { const int orow = att::crow(r, hi); const float f = ws[orow];
; #pragma unroll
;         for (int d0 = 0; d0 < 4; ++d0) { bf16_t* p = stg + orow * 136 + d0 * 32 + r32; float v = c.o[d0][r] * f; if (!first) v += bf2f(*p); *p = f2bf1(v); } }
;     LDS_WAIT();
; }
; DI void nsa_attention(int L2, char* lds, int vcu, int G, int tid, int wave, int lane) {
;     ...
;             att::core_reset<128>(c, att::M_INIT, 0.f);
;             SeqRange seq; seq.lo = qt - 8 < 0 ? 0 : qt - 8; seq.hi = qt;
	v_lshlrev_b32_e32 v2, 16, v2
	v_fmac_f32_e32 v2, v47, v0
	v_cvt_pk_bf16_f32 v2, v2, v1
	ds_write_b16 v202, v2 offset:1696
	ds_read_u16 v2, v202 offset:1760
	v_mov_b32_e32 v47, 0
	s_waitcnt lgkmcnt(0)
	v_lshlrev_b32_e32 v2, 16, v2
	v_fmac_f32_e32 v2, v31, v0
	v_cvt_pk_bf16_f32 v2, v2, v1
	ds_write_b16 v202, v2 offset:1760
	ds_read_u16 v2, v202 offset:1824
	v_mov_b32_e32 v31, 0
	s_waitcnt lgkmcnt(0)
	v_lshlrev_b32_e32 v2, 16, v2
	v_fmac_f32_e32 v2, v15, v0
	v_cvt_pk_bf16_f32 v0, v2, v1
	ds_write_b16 v202, v0 offset:1824
	ds_read_b32 v0, v182 offset:104
	ds_read_u16 v2, v202 offset:1904
	v_mov_b32_e32 v15, 0
	s_waitcnt lgkmcnt(0)
	v_lshlrev_b32_e32 v2, 16, v2
	v_fmac_f32_e32 v2, v64, v0
	v_cvt_pk_bf16_f32 v2, v2, v1
	ds_write_b16 v202, v2 offset:1904
	ds_read_u16 v2, v202 offset:1968
	v_mov_b32_e32 v64, 0
	s_waitcnt lgkmcnt(0)
	v_lshlrev_b32_e32 v2, 16, v2
	v_fmac_f32_e32 v2, v48, v0
	v_cvt_pk_bf16_f32 v2, v2, v1
	ds_write_b16 v202, v2 offset:1968
	ds_read_u16 v2, v202 offset:2032
	v_mov_b32_e32 v48, 0
	s_waitcnt lgkmcnt(0)
	v_lshlrev_b32_e32 v2, 16, v2
	v_fmac_f32_e32 v2, v32, v0
	v_cvt_pk_bf16_f32 v2, v2, v1
	ds_write_b16 v202, v2 offset:2032
	ds_read_u16 v2, v202 offset:2096
	v_mov_b32_e32 v32, 0
	s_waitcnt lgkmcnt(0)
	v_lshlrev_b32_e32 v2, 16, v2
	v_fmac_f32_e32 v2, v16, v0
	v_cvt_pk_bf16_f32 v0, v2, v1
	ds_write_b16 v202, v0 offset:2096
	ds_read_b32 v0, v182 offset:108
	ds_read_u16 v2, v202 offset:2176
	v_mov_b32_e32 v16, 0
	s_waitcnt lgkmcnt(0)
	v_lshlrev_b32_e32 v2, 16, v2
	v_fmac_f32_e32 v2, v65, v0
	v_cvt_pk_bf16_f32 v2, v2, v1
	ds_write_b16 v202, v2 offset:2176
	ds_read_u16 v2, v202 offset:2240
	v_mov_b32_e32 v65, 0
	s_waitcnt lgkmcnt(0)
	v_lshlrev_b32_e32 v2, 16, v2
	v_fmac_f32_e32 v2, v49, v0
	v_cvt_pk_bf16_f32 v2, v2, v1
	ds_write_b16 v202, v2 offset:2240
	ds_read_u16 v2, v202 offset:2304
	v_mov_b32_e32 v49, 0
	s_waitcnt lgkmcnt(0)
	v_lshlrev_b32_e32 v2, 16, v2
	v_fmac_f32_e32 v2, v33, v0
	v_cvt_pk_bf16_f32 v2, v2, v1
	ds_write_b16 v202, v2 offset:2304
	ds_read_u16 v2, v202 offset:2368
	v_mov_b32_e32 v33, 0
	s_waitcnt lgkmcnt(0)
	v_lshlrev_b32_e32 v2, 16, v2
	v_fmac_f32_e32 v2, v17, v0
	v_cvt_pk_bf16_f32 v0, v2, v1
	ds_write_b16 v202, v0 offset:2368
	s_waitcnt lgkmcnt(0)
	v_mov_b32_e32 v17, 0
	v_mov_b32_e32 v2, 0
	s_load_dwordx2 s[12:13], s[0:1], 0xc8
	s_waitcnt lgkmcnt(0)
	s_load_dwordx2 s[2:3], s[0:1], 0xc8
	s_waitcnt lgkmcnt(0)
	s_cbranch_scc1 .LBB0_898
; DI int v_rd_base(int lane) { return ((lane & 3) << 3) | (((lane >> 2) & 3) << 6) | (((lane >> 4) & 1) << 5) | (((lane >> 5) & 1) << 8); }
; #define LBAR() asm volatile("s_waitcnt lgkmcnt(0)\n\ts_barrier" ::: "memory")
; template <int D, bool PIPE, class Seq, class MaskF, class KX>
; DI void run_tiles(Core<D>& c, char* kv, float* ws, const bf16_t* Kg0, const bf16_t* Vg0, int pitch, const Seq& seq, const MaskF& mk, const KX& kx, int tid_, int lane_) {
;     ...
;     int t0; if (!seq.first(t0)) return;
;     const int vb0 = (int)(uintptr_t)(kv + 2 * KB) + v_rd_base(lane);
;     StgH<D> sk, sv;
;     if constexpr (!PIPE) {
;         stg_ld<D>(sk, Kg0 + (size_t)64 * t0 * pitch, pitch, tid); stg_ld<D>(sv, Vg0 + (size_t)64 * t0 * pitch, pitch, tid);
;         LBAR();
;         kx.apply(sk, t0, tid); stg_wrK<D>(sk, kv, tid); stg_wrV<D>(sv, kv + 2 * KB, tid);
;         LBAR();
; DI void nsa_attention(int L2, char* lds, int vcu, int G, int tid, int wave, int lane) {
;     ...
;             att::core_reset<128>(c, att::M_INIT, 0.f);
;             SeqRange seq; seq.lo = qt - 8 < 0 ? 0 : qt - 8; seq.hi = qt;
;             MaskWin mk; mk.t = t; mk.w = 512; mk.tmin = t0; mk.tmax = t0 + 63;
;             att::run_tiles<128, false>(c, lds + NSL_KV, ws, NSA_QKV + (size_t)b * T * NS_N + NS_KW + g * 128, NSA_QKV + (size_t)b * T * NS_N + NS_VW + g * 128, NS_N, seq, mk, KxNone(), tid, lane);
	s_lshl_b64 s[14:15], s[48:49], 1
	s_add_u32 s4, s12, s14
	s_addc_u32 s5, s13, s15
	s_lshl_b32 s10, s56, 1
	s_add_u32 s4, s4, s10
	s_addc_u32 s5, s5, 0
	s_add_u32 s94, s4, 0x2fb02000
	s_addc_u32 s4, s5, 0
	s_add_u32 s2, s2, s14
	s_addc_u32 s3, s3, s15
	s_add_u32 s2, s2, s10
	s_addc_u32 s3, s3, 0
	s_add_u32 s5, s2, 0x2fb02400
	v_ashrrev_i32_e32 v3, 4, v67
	s_addc_u32 s85, s3, 0
	s_mul_i32 s14, s92, 0xa0000
	s_movk_i32 s15, 0x1400
	v_add_u32_e32 v9, 32, v3
	s_mul_hi_u32 s10, s92, 0xa0000
	s_add_u32 s2, s94, s14
	v_lshlrev_b32_e32 v8, 3, v67
	v_mad_i64_i32 v[4:5], s[12:13], v3, s15, 0
	v_mad_i64_i32 v[6:7], s[12:13], v9, s15, 0
	s_addc_u32 s3, s4, s10
	v_and_b32_e32 v2, 0x78, v8
	v_lshlrev_b64 v[170:171], 1, v[4:5]
	v_lshlrev_b64 v[172:173], 1, v[6:7]
	v_lshl_add_u64 v[4:5], s[2:3], 0, v[170:171]
	v_lshlrev_b32_e32 v0, 1, v2
	v_lshl_add_u64 v[6:7], s[2:3], 0, v[172:173]
	s_add_u32 s2, s5, s14
	v_lshl_add_u64 v[4:5], v[4:5], 0, v[0:1]
	s_addc_u32 s3, s85, s10
	v_lshl_add_u64 v[6:7], v[6:7], 0, v[0:1]
	global_load_dwordx4 v[98:101], v[4:5], off
	global_load_dwordx4 v[102:105], v[6:7], off
	v_lshl_add_u64 v[4:5], s[2:3], 0, v[170:171]
	v_lshl_add_u64 v[4:5], v[4:5], 0, v[0:1]
	v_lshl_add_u64 v[6:7], s[2:3], 0, v[172:173]
	v_lshl_add_u64 v[6:7], v[6:7], 0, v[0:1]
	global_load_dwordx4 v[106:109], v[4:5], off
	global_load_dwordx4 v[144:147], v[6:7], off
	v_ashrrev_i32_e32 v0, 5, v66
	v_and_b32_e32 v4, 31, v66
	v_lshlrev_b32_e32 v6, 4, v66
	v_and_b32_e32 v13, 0xfffff0, v3
	v_lshlrev_b32_e32 v14, 1, v3
	v_and_b32_e32 v12, 0xc0, v6
	v_lshlrev_b32_e32 v175, 8, v4
	v_and_b32_e32 v176, 0xf0, v6
	v_lshlrev_b32_e32 v177, 4, v0
	v_lshlrev_b32_e32 v203, 2, v0
	v_lshl_add_u32 v204, v4, 2, s11
	v_and_or_b32 v0, v14, 8, v13
	v_and_b32_e32 v4, 0xfffff0, v9
	v_lshlrev_b32_e32 v6, 1, v9
	v_lshrrev_b32_e32 v15, 1, v3
	v_bfe_u32 v8, v8, 5, 2
	v_and_b32_e32 v3, 3, v3
	v_lshrrev_b32_e32 v0, 1, v0
	v_and_or_b32 v4, v6, 8, v4
	v_lshlrev_b32_e32 v10, 4, v67
	v_and_b32_e32 v11, 0xf0, v67
	s_movk_i32 s2, 0xf0
	v_and_or_b32 v3, v15, 4, v3
	v_or_b32_e32 v0, v0, v8
	v_lshrrev_b32_e32 v4, 1, v4
	v_lshlrev_b32_e32 v7, 1, v66
	v_bitop3_b32 v11, v10, v11, s2 bitop3:0x6c
	v_and_b32_e32 v16, 48, v10
	s_movk_i32 s2, 0xff00
	v_lshlrev_b32_e32 v3, 6, v3
	v_lshlrev_b32_e32 v0, 9, v0
	v_or_b32_e32 v4, v4, v8
	v_lshlrev_b32_e32 v5, 3, v66
	v_and_b32_e32 v7, 32, v7
	v_and_or_b32 v205, v10, s2, v11
	s_movk_i32 s2, 0x118
	v_or3_b32 v212, v0, v3, v16
	v_lshlrev_b32_e32 v0, 9, v4
	v_and_or_b32 v5, v5, s2, v7
	v_add_u32_e32 v7, 0, v205
	v_or3_b32 v213, v0, v3, v16
	s_add_i32 s90, s86, 0xfffffe3f
	s_add_i32 s2, 0, 0x8000
	v_add_u32_e32 v4, 0, v212
	v_add_u32_e32 v0, 0, v213
	s_waitcnt lgkmcnt(0)
	s_barrier
	s_cmp_lg_u32 s2, -1
	v_writelane_b32 v255, s80, 22
	s_cselect_b32 s2, s2, 0
	v_mov_b32_e32 v50, v1
	v_mov_b32_e32 v51, v1
	v_writelane_b32 v255, s79, 25
	v_add3_u32 v214, v12, s2, v5
	v_mov_b32_e32 v52, v1
	v_mov_b32_e32 v53, v1
	v_mov_b32_e32 v54, v1
	v_mov_b32_e32 v55, v1
	s_waitcnt vmcnt(3)
	ds_write_b128 v7, v[98:101]
	s_waitcnt vmcnt(2)
	ds_write_b128 v7, v[102:105] offset:8192
	s_waitcnt vmcnt(1)
	ds_write_b128 v4, v[106:109] offset:32768
	s_waitcnt vmcnt(0)
	ds_write_b128 v0, v[144:147] offset:32768
	s_waitcnt lgkmcnt(0)
	s_barrier
	v_mov_b32_e32 v56, v1
	v_mov_b32_e32 v57, v1
	v_mov_b32_e32 v58, v1
	v_mov_b32_e32 v59, v1
	v_mov_b32_e32 v60, v1
	v_mov_b32_e32 v61, v1
	v_mov_b32_e32 v62, v1
	v_mov_b32_e32 v63, v1
	v_mov_b32_e32 v64, v1
	v_mov_b32_e32 v65, v1
	v_lshlrev_b32_e32 v0, 1, v2
	v_mov_b64_e32 v[34:35], v[50:51]
	v_mov_b64_e32 v[18:19], v[50:51]
	v_mov_b64_e32 v[2:3], v[50:51]
	v_writelane_b32 v255, s78, 21
	s_mov_b32 s84, 0x42b504f3
	v_cmp_gt_u32_e64 s[12:13], 32, v66
	v_add_u32_e32 v174, 0xfffffe00, v169
	v_add_u32_e32 v206, 0x60, v177
	v_add_u32_e32 v207, 0x80, v177
	v_add_u32_e32 v208, 0xa0, v177
	v_add_u32_e32 v209, 0xc0, v177
	v_add_u32_e32 v210, 0xe0, v177
	v_add_u32_e32 v211, s11, v177
	s_mov_b32 s10, 0
	v_mov_b32_e32 v216, 0
	v_mov_b32_e32 v215, 0xc6ea6000
	v_mov_b64_e32 v[36:37], v[52:53]
	v_mov_b64_e32 v[38:39], v[54:55]
	v_mov_b64_e32 v[40:41], v[56:57]
	v_mov_b64_e32 v[42:43], v[58:59]
	v_mov_b64_e32 v[44:45], v[60:61]
	v_mov_b64_e32 v[46:47], v[62:63]
	v_mov_b64_e32 v[48:49], v[64:65]
	v_mov_b64_e32 v[20:21], v[52:53]
	v_mov_b64_e32 v[22:23], v[54:55]
	v_mov_b64_e32 v[24:25], v[56:57]
	v_mov_b64_e32 v[26:27], v[58:59]
	v_mov_b64_e32 v[28:29], v[60:61]
	v_mov_b64_e32 v[30:31], v[62:63]
	v_mov_b64_e32 v[32:33], v[64:65]
	v_mov_b64_e32 v[4:5], v[52:53]
	v_mov_b64_e32 v[6:7], v[54:55]
	v_mov_b64_e32 v[8:9], v[56:57]
	v_mov_b64_e32 v[10:11], v[58:59]
	v_mov_b64_e32 v[12:13], v[60:61]
	v_mov_b64_e32 v[14:15], v[62:63]
	v_mov_b64_e32 v[16:17], v[64:65]
